# attnC loop back edge rotated: next tile's LDS addresses and ring rotation computed before the barrier, fragment reads lead the post-barrier segment, DMA issue after them
# baseline (speedup 1.0000x reference)
; #define LAS __attribute__((address_space(3)))
; __device__ __forceinline__ void attnC_unit(const Args& a, int unit, LAS unsigned char* lds) {
;     ...
;     const int srow = tid >> 3, sch = tid & 7;
;     const unsigned char* kg = (const unsigned char*)(P + ((size_t)b * SEQ + srow) * PW + CK0 + 64 * g) + sch * 16;
;     const unsigned char* vg = (const unsigned char*)(P + ((size_t)b * SEQ + srow) * PW + CV0 + 64 * g) + sch * 16;
;     const int kwo = srow * 128 + ((sch ^ ((srow >> 1) & 7)) * 16), vwo = 8192 + srow * 128 + sch * 16;
;     const size_t tok0 = (size_t)b * SEQ + 512 * qb + 64 * wid + ql;
;     bf16x8 qf[2][4]; f32x16 o0[2], o1[2]; float m[2], l[2];
; #pragma unroll
;     for (int e = 0; e < 2; ++e) {
;         const bf16_t* qp = P + (tok0 + 32 * e) * PW + CQ0 + 64 * hq + 8 * h;
; #pragma unroll
;         for (int s = 0; s < 4; ++s) qf[e][s] = *(const bf16x8*)(qp + 16 * s);
; #pragma unroll
;         for (int i = 0; i < 16; ++i) { o0[e][i] = 0.f; o1[e][i] = 0.f; }
;         m[e] = -1e30f; l[e] = 0.f;
;     }
;     constexpr size_t TSTEP = (size_t)64 * PW * 2;
;     u32x4 rk = *(const u32x4*)kg, rv = *(const u32x4*)vg;
;     __syncthreads();
;     *(LAS u32x4*)(lds + kwo) = rk; *(LAS u32x4*)(lds + vwo) = rv;
;     rk = *(const u32x4*)(kg + TSTEP); rv = *(const u32x4*)(vg + TSTEP);
;     __syncthreads();
.LaN_entry:
	s_waitcnt vmcnt(0)
	v_add_u32_e32 v142, 0x4000, v250
	v_add_u32_e32 v143, 0x4000, v251
	ds_write_b128 v142, v[112:115]
	ds_write_b128 v143, v[116:119] offset:8192
	v_and_b32_e32 v142, 7, v225
	v_bfe_u32 v143, v225, 4, 3
	v_xor_b32_e32 v143, v143, v142
	v_sub_u32_e32 v143, v143, v142
	v_lshlrev_b32_e32 v143, 4, v143
	v_add_u32_e32 v143, 0xffffff00, v143
	v_ashrrev_i32_e32 v144, 31, v143
	v_add_co_u32_e32 v198, vcc, v180, v143
	s_nop 0
	v_addc_co_u32_e32 v199, vcc, v181, v144, vcc
	v_readfirstlane_b32 s28, v225
	s_lshl_b32 s28, s28, 4
	s_mov_b32 s29, 0
	s_movk_i32 s30, 0x4000
	s_mov_b32 s31, 0x8000
	s_mov_b32 s3, 0
	v_mov_b32_e32 v182, 0
	v_mov_b32_e32 v183, 0
	v_mov_b32_e32 v184, 0
	v_mov_b32_e32 v185, 0
	v_mov_b32_e32 v186, 0
	v_mov_b32_e32 v187, 0
	v_mov_b32_e32 v188, 0
	v_mov_b32_e32 v189, 0
	v_mov_b32_e32 v190, 0
	v_mov_b32_e32 v191, 0
	v_mov_b32_e32 v192, 0
	v_mov_b32_e32 v193, 0
	v_mov_b32_e32 v194, 0
	v_mov_b32_e32 v195, 0
	v_mov_b32_e32 v196, 0
	v_mov_b32_e32 v197, 0
	v_mov_b32_e32 v120, 0
	v_mov_b32_e32 v121, 0
	v_mov_b32_e32 v122, 0
	v_mov_b32_e32 v123, 0
	v_mov_b32_e32 v124, 0
	v_mov_b32_e32 v125, 0
	v_mov_b32_e32 v126, 0
	v_mov_b32_e32 v127, 0
	v_mov_b32_e32 v128, 0
	v_mov_b32_e32 v129, 0
	v_mov_b32_e32 v130, 0
	v_mov_b32_e32 v131, 0
	v_mov_b32_e32 v132, 0
	v_mov_b32_e32 v133, 0
	v_mov_b32_e32 v134, 0
	v_mov_b32_e32 v135, 0
	s_waitcnt lgkmcnt(0)
	s_mov_b32 s34, 0x71800000
	v_add3_u32 v137, s29, v157, v156
	v_add3_u32 v142, s29, v252, v231
	v_add3_u32 v143, s29, v252, v239
	v_add3_u32 v144, s29, v252, v232
	v_add3_u32 v145, s29, v252, v241

; #define LAS __attribute__((address_space(3)))
; __device__ __forceinline__ void attnC_unit(const Args& a, int unit, LAS unsigned char* lds) {
;     ...
;     for (int kt = 0; kt < 32; ++kt) {
;         LAS unsigned char* cur = lds + (kt & 1) * 16384;
;         LAS unsigned char* nxt = lds + ((kt + 1) & 1) * 16384;
;         if (kt + 1 < 32) { *(LAS u32x4*)(nxt + kwo) = rk; *(LAS u32x4*)(nxt + vwo) = rv; }
;         if (kt + 2 < 32) { rk = *(const u32x4*)(kg + (size_t)(kt + 2) * TSTEP); rv = *(const u32x4*)(vg + (size_t)(kt + 2) * TSTEP); }
; #pragma unroll
;         for (int j = 0; j < 2; ++j) {
;             bf16x8 kf[4], vf[2][2];
;             load_kf(cur + j * 4096, kf, lane); load_vf(cur + 8192 + j * 4096, vf, lane);
; #pragma unroll
;             for (int e = 0; e < 2; ++e) attn_step<false>(kf, cur, vf, qf[e], o0[e], o1[e], m[e], l[e], lane, 0);
.LaN_wd:
	s_barrier
	ds_read_b128 v[112:115], v142
	ds_read_b128 v[116:119], v143
	ds_read_b128 v[216:219], v144
	ds_read_b128 v[220:223], v145
	ds_read_b64_tr_b16 v[146:147], v137 offset:8192
	ds_read_b64_tr_b16 v[148:149], v137 offset:9216
	ds_read_b64_tr_b16 v[204:205], v137 offset:8256
	ds_read_b64_tr_b16 v[206:207], v137 offset:9280
	ds_read_b64_tr_b16 v[208:209], v137 offset:10240
	ds_read_b64_tr_b16 v[210:211], v137 offset:11264
	ds_read_b64_tr_b16 v[212:213], v137 offset:10304
	ds_read_b64_tr_b16 v[214:215], v137 offset:11328
	s_cmp_lt_u32 s3, 30
	s_cbranch_scc0 .LaN_nd
	s_add_i32 s33, s31, s28
	s_mov_b32 m0, s33
	s_nop 0
	global_load_lds_dwordx4 v[198:199], off
	s_add_i32 m0, s33, 0x2000
	s_nop 0
	global_load_lds_dwordx4 v[180:181], off
	v_lshl_add_u64 v[198:199], v[198:199], 0, s[18:19]
	v_lshl_add_u64 v[180:181], v[180:181], 0, s[18:19]
.LaN_nd:
	s_waitcnt lgkmcnt(11)
	v_mfma_f32_32x32x16_bf16 v[64:79], v[112:115], v[80:83], v[182:197]
	v_mfma_f32_32x32x16_bf16 v[158:173], v[112:115], v[96:99], v[120:135]
	s_waitcnt lgkmcnt(10)
	v_mfma_f32_32x32x16_bf16 v[64:79], v[116:119], v[84:87], v[64:79]
	v_mfma_f32_32x32x16_bf16 v[158:173], v[116:119], v[100:103], v[158:173]
	s_waitcnt lgkmcnt(9)
	v_mfma_f32_32x32x16_bf16 v[64:79], v[216:219], v[88:91], v[64:79]
	v_mfma_f32_32x32x16_bf16 v[158:173], v[216:219], v[104:107], v[158:173]
	s_waitcnt lgkmcnt(8)
	v_mfma_f32_32x32x16_bf16 v[64:79], v[220:223], v[92:95], v[64:79]
	v_mfma_f32_32x32x16_bf16 v[158:173], v[220:223], v[108:111], v[158:173]
	s_nop 10
	s_cmp_eq_u32 s3, 0
	s_cbranch_scc1 .LaN_fs

; __device__ __forceinline__ unsigned pk2n(float lo, float hi) { const f32x2v v = {lo, hi}; const bf16v2 b = __builtin_convertvector(v, bf16v2); return __builtin_bit_cast(unsigned, b); }
; __device__ __forceinline__ float fexp2(float x) { return __builtin_amdgcn_exp2f(x); }
; template <bool KLDS>
; __device__ __forceinline__ void attn_step(const bf16x8 (&kf)[4], LAS const unsigned char* kb, const bf16x8 (&vf)[2][2], const bf16x8 (&qf)[4], f32x16& o0, f32x16& o1, float& m, float& l, int lane, int maskmode) {
;     ...
;     const float mn = fmaxf(m, tm), al = fexp2(m - mn); m = mn;
;     float ps = 0.f;
; #pragma unroll
;     for (int i = 0; i < 16; ++i) { S[i] = fexp2(S[i] - mn); ps += S[i]; }
;     l = l * al + ps;
; #pragma unroll
;     for (int i = 0; i < 16; ++i) { o0[i] *= al; o1[i] *= al; }
;     bf16x8 pf[2];
; #pragma unroll
;     for (int s2 = 0; s2 < 2; ++s2) {
;         u32x4 w; w.x = pk2n(S[8 * s2 + 0], S[8 * s2 + 1]); w.y = pk2n(S[8 * s2 + 2], S[8 * s2 + 3]); w.z = pk2n(S[8 * s2 + 4], S[8 * s2 + 5]); w.w = pk2n(S[8 * s2 + 6], S[8 * s2 + 7]);
;         pf[s2] = __builtin_bit_cast(bf16x8, w);
;     }
; #pragma unroll
;     for (int s2 = 0; s2 < 2; ++s2) {
;         o0 = __builtin_amdgcn_mfma_f32_32x32x16_bf16(vf[s2][0], pf[s2], o0, 0, 0, 0);
;         o1 = __builtin_amdgcn_mfma_f32_32x32x16_bf16(vf[s2][1], pf[s2], o1, 0, 0, 0);
;     }
.LaN_xj1:
	v_exp_f32_e32 v64, v64
	v_exp_f32_e32 v158, v158
	v_exp_f32_e32 v65, v65
	v_exp_f32_e32 v159, v159
	v_exp_f32_e32 v66, v66
	v_exp_f32_e32 v160, v160
	v_add_f32_e32 v138, v64, v65
	v_add_f32_e32 v140, v158, v159
	v_exp_f32_e32 v67, v67
	v_exp_f32_e32 v161, v161
	v_add_f32_e32 v139, v66, v67
	v_add_f32_e32 v141, v160, v161
	v_exp_f32_e32 v68, v68
	v_exp_f32_e32 v162, v162
	v_exp_f32_e32 v69, v69
	v_exp_f32_e32 v163, v163
	v_add_f32_e32 v139, v139, v68
	v_add_f32_e32 v141, v141, v162
	v_exp_f32_e32 v70, v70
	v_exp_f32_e32 v164, v164
	v_add_f32_e32 v138, v138, v69
	v_add_f32_e32 v140, v140, v163
	v_exp_f32_e32 v71, v71
	v_exp_f32_e32 v165, v165
	v_add_f32_e32 v139, v139, v70
	v_add_f32_e32 v141, v141, v164
	v_exp_f32_e32 v72, v72
	v_exp_f32_e32 v166, v166
	v_add_f32_e32 v138, v138, v71
	v_add_f32_e32 v140, v140, v165
	v_exp_f32_e32 v73, v73
	v_exp_f32_e32 v167, v167
	v_add_f32_e32 v139, v139, v72
	v_add_f32_e32 v141, v141, v166
	v_exp_f32_e32 v74, v74
	v_exp_f32_e32 v168, v168
	v_add_f32_e32 v138, v138, v73
	v_add_f32_e32 v140, v140, v167
	v_exp_f32_e32 v75, v75
	v_exp_f32_e32 v169, v169
	v_add_f32_e32 v139, v139, v74
	v_add_f32_e32 v141, v141, v168
	v_exp_f32_e32 v76, v76
	v_exp_f32_e32 v170, v170
	v_add_f32_e32 v138, v138, v75
	v_add_f32_e32 v140, v140, v169
	v_exp_f32_e32 v77, v77
	v_exp_f32_e32 v171, v171
	v_add_f32_e32 v139, v139, v76
	v_add_f32_e32 v141, v141, v170
	v_exp_f32_e32 v78, v78
	v_exp_f32_e32 v172, v172
	v_add_f32_e32 v138, v138, v77
	v_add_f32_e32 v140, v140, v171
	v_exp_f32_e32 v79, v79
	v_exp_f32_e32 v173, v173
	v_add_f32_e32 v139, v139, v78
	v_add_f32_e32 v141, v141, v172
	s_nop 0
	s_nop 0
	v_add_f32_e32 v139, v139, v79
	v_add_f32_e32 v141, v141, v173
	v_add_f32_e32 v138, v138, v139
	v_add_f32_e32 v140, v140, v141
	v_cmp_lt_f32_e64 s[10:11], s34, v138
	v_cmp_lt_f32_e64 s[4:5], s34, v140
	s_nop 0
	s_or_b64 vcc, s[10:11], s[4:5]
	s_cbranch_vccnz .LaN_ovj1
	v_add_f32_e32 v179, v179, v138
	v_add_f32_e32 v178, v178, v140
	v_cvt_pk_bf16_f32 v64, v64, v65
	v_cvt_pk_bf16_f32 v158, v158, v159
	v_cvt_pk_bf16_f32 v65, v66, v67
	v_cvt_pk_bf16_f32 v159, v160, v161
	v_cvt_pk_bf16_f32 v66, v68, v69
	v_cvt_pk_bf16_f32 v160, v162, v163
	v_cvt_pk_bf16_f32 v67, v70, v71
	v_cvt_pk_bf16_f32 v161, v164, v165
	v_cvt_pk_bf16_f32 v68, v72, v73
	v_cvt_pk_bf16_f32 v162, v166, v167
	v_cvt_pk_bf16_f32 v69, v74, v75
	v_cvt_pk_bf16_f32 v163, v168, v169
	v_cvt_pk_bf16_f32 v70, v76, v77
	v_cvt_pk_bf16_f32 v164, v170, v171
	v_cvt_pk_bf16_f32 v71, v78, v79
	v_cvt_pk_bf16_f32 v165, v172, v173
	s_waitcnt lgkmcnt(0)
	v_mfma_f32_32x32x16_bf16 v[48:63], v[146:149], v[64:67], v[48:63]
	v_mfma_f32_32x32x16_bf16 v[16:31], v[146:149], v[158:161], v[16:31]
	v_mfma_f32_32x32x16_bf16 v[32:47], v[204:207], v[64:67], v[32:47]
	v_mfma_f32_32x32x16_bf16 v[0:15], v[204:207], v[158:161], v[0:15]
	v_mfma_f32_32x32x16_bf16 v[48:63], v[208:211], v[68:71], v[48:63]
	v_mfma_f32_32x32x16_bf16 v[16:31], v[208:211], v[162:165], v[16:31]
	v_mfma_f32_32x32x16_bf16 v[32:47], v[212:215], v[68:71], v[32:47]
	v_mfma_f32_32x32x16_bf16 v[0:15], v[212:215], v[162:165], v[0:15]
	s_mov_b32 s33, s29
	s_mov_b32 s29, s30
	s_mov_b32 s30, s31
	s_mov_b32 s31, s33
	s_add_i32 s3, s3, 1
	v_add3_u32 v137, s29, v157, v156
	v_add3_u32 v142, s29, v252, v231
	v_add3_u32 v143, s29, v252, v239
	v_add3_u32 v144, s29, v252, v232
	v_add3_u32 v145, s29, v252, v241
	s_cmp_lg_u32 s3, 32
	s_cbranch_scc1 .LaN_loop
	s_nop 15
	s_nop 7
	s_branch .LBB0_252
